# SWIGLU/MIX row statistics loaded inside the last K-iteration; epilogue waits vmcnt(6) leaving the next unit's stage loads in flight
# baseline (speedup 1.0000x reference)
; #define PG8_STAGE(bufoff, gbase, voff) do { _Pragma("unroll") for (int _i = 0; _i < 2; ++_i) \
;         __builtin_amdgcn_global_load_lds((const unsigned*)((const char*)(gbase) + (voff)[_i]), (PG8_LAS unsigned*)(lds + (bufoff) + ldsw + _i * 8192), 16, 0, 0); } while (0)
; #define PG8_LDA(dst, b, h) do { _Pragma("unroll") for (int m = 0; m < 4; ++m) _Pragma("unroll") for (int k = 0; k < 2; ++k) dst[m][k] = *(const PG8_LAS bf16x8*)(lds + PG8_SA(b, h) + aoff + m * 2048 + k * 1024); } while (0)
; #define PG8_LDB(dst, b, h) do { _Pragma("unroll") for (int n = 0; n < 2; ++n) _Pragma("unroll") for (int k = 0; k < 2; ++k) dst[n][k] = *(const PG8_LAS bf16x8*)(lds + PG8_SB(b, h) + boff + n * 2048 + k * 1024); } while (0)
; #define PG8_MMA(ai, bj, At, Bt) do { __builtin_amdgcn_s_setprio(1); _Pragma("unroll") for (int m = 0; m < 4; ++m) _Pragma("unroll") for (int n = 0; n < 2; ++n) _Pragma("unroll") for (int k = 0; k < 2; ++k) \
;         acc[ai][bj][m][n] = __builtin_amdgcn_mfma_f32_16x16x32_bf16(Bt[n][k], At[m][k], acc[ai][bj][m][n], 0, 0, 0); __builtin_amdgcn_s_setprio(0); } while (0)
; #define PG8_WAIT_V(n) asm volatile("s_waitcnt vmcnt(" #n ")" ::: "memory")
; #define PG8_WAIT_L(n) asm volatile("s_waitcnt lgkmcnt(" #n ")" ::: "memory")
; #define PG8_BAR __builtin_amdgcn_s_barrier()
; #define PG8_SCHED __builtin_amdgcn_sched_barrier(0)
; template <class Epi, class Sched, bool ALIGN_EPI = false, bool SP2 = false>
; __device__ __forceinline__ void gemm_phase(PG8_LAS unsigned char* lds, const Gemm g, const Sched& S, const Epi& E, const int wid_) {
;     ...
;             PG8_LDB(B0, 0, 0); PG8_LDB(B1, 0, 1); PG8_SCHED; PG8_LDA(At, 0, 0); PG8_STAGE(PG8_SA(1, 1), a1 + hstepA, voffA);
;             PG8_WAIT_V(8); PG8_WAIT_L(0); PG8_BAR; PG8_MMA(0, 0, At, B0); PG8_MMA(0, 1, At, B1); PG8_BAR; PG8_SCHED;
;             PG8_LDA(At, 0, 1); PG8_STAGE(PG8_SB(0, 0), b2, voffB); PG8_STAGE(PG8_SB(0, 1), b2 + hstepB, voffB); PG8_STAGE(PG8_SA(0, 0), a2, voffA);
;             PG8_WAIT_V(8); PG8_WAIT_L(0); PG8_BAR; PG8_MMA(1, 0, At, B0); PG8_MMA(1, 1, At, B1); PG8_BAR; PG8_SCHED;
.LBB0_380:
	s_add_i32 s97, s38, 2
	s_add_u32 s98, s6, 0x80
	s_addc_u32 s39, s7, 0
	s_cmp_eq_u32 s41, s38
	s_cselect_b32 s39, s47, s39
	s_cselect_b32 s38, s46, s98
	s_cselect_b32 s99, s61, s62
	s_cselect_b32 s98, s60, s49
	s_add_i32 vcc_lo, 0, 0x14000
	v_add_u32_e32 v164, s42, v180
	v_add_u32_e32 v176, vcc_lo, v180
	ds_read_b128 v[128:131], v164
	ds_read_b128 v[132:135], v164 offset:1024
	ds_read_b128 v[136:139], v164 offset:2048
	ds_read_b128 v[164:167], v164 offset:3072
	ds_read_b128 v[168:171], v176
	ds_read_b128 v[172:175], v176 offset:1024
	ds_read_b128 v[182:185], v176 offset:2048
	ds_read_b128 v[186:189], v176 offset:3072
	v_lshl_add_u64 v[178:179], s[6:7], 0, v[162:163]
	s_add_i32 m0, s36, 0xc000
	ds_read_b128 v[190:193], v181
	ds_read_b128 v[194:197], v181 offset:1024
	ds_read_b128 v[198:201], v181 offset:2048
	ds_read_b128 v[202:205], v181 offset:3072
	ds_read_b128 v[206:209], v181 offset:4096
	ds_read_b128 v[212:215], v181 offset:5120
	ds_read_b128 v[216:219], v181 offset:6144
	ds_read_b128 v[220:223], v181 offset:7168
	global_load_lds_dwordx4 v[178:179], off
	v_lshl_add_u64 v[178:179], s[6:7], 0, v[160:161]
	s_add_i32 m0, s36, 0xe000
	s_nop 0
	global_load_lds_dwordx4 v[178:179], off
	s_waitcnt vmcnt(8)
	s_waitcnt lgkmcnt(0)
	s_barrier
	s_waitcnt lgkmcnt(0)
	v_mfma_f32_16x16x32_bf16 v[124:127], v[128:131], v[190:193], v[124:127]
	v_mfma_f32_16x16x32_bf16 v[120:123], v[136:139], v[190:193], v[120:123]
	v_mfma_f32_16x16x32_bf16 v[116:119], v[128:131], v[198:201], v[116:119]
	v_mfma_f32_16x16x32_bf16 v[112:115], v[136:139], v[198:201], v[112:115]
	v_mfma_f32_16x16x32_bf16 v[100:103], v[128:131], v[206:209], v[100:103]
	v_mfma_f32_16x16x32_bf16 v[96:99], v[136:139], v[206:209], v[96:99]
	v_mfma_f32_16x16x32_bf16 v[84:87], v[128:131], v[216:219], v[84:87]
	v_mfma_f32_16x16x32_bf16 v[80:83], v[136:139], v[216:219], v[80:83]
	v_mfma_f32_16x16x32_bf16 v[124:127], v[132:135], v[194:197], v[124:127]
	v_mfma_f32_16x16x32_bf16 v[120:123], v[164:167], v[194:197], v[120:123]
	v_mfma_f32_16x16x32_bf16 v[116:119], v[132:135], v[202:205], v[116:119]
	v_mfma_f32_16x16x32_bf16 v[112:115], v[164:167], v[202:205], v[112:115]
	v_mfma_f32_16x16x32_bf16 v[100:103], v[132:135], v[212:215], v[100:103]
	v_mfma_f32_16x16x32_bf16 v[96:99], v[164:167], v[212:215], v[96:99]
	v_mfma_f32_16x16x32_bf16 v[84:87], v[132:135], v[220:223], v[84:87]
	v_mfma_f32_16x16x32_bf16 v[80:83], v[164:167], v[220:223], v[80:83]
	v_mfma_f32_16x16x32_bf16 v[108:111], v[168:171], v[190:193], v[108:111]
	v_mfma_f32_16x16x32_bf16 v[104:107], v[182:185], v[190:193], v[104:107]
	v_mfma_f32_16x16x32_bf16 v[92:95], v[168:171], v[198:201], v[92:95]
	v_mfma_f32_16x16x32_bf16 v[88:91], v[182:185], v[198:201], v[88:91]
	v_mfma_f32_16x16x32_bf16 v[76:79], v[168:171], v[206:209], v[76:79]
	v_mfma_f32_16x16x32_bf16 v[72:75], v[182:185], v[206:209], v[72:75]
	v_mfma_f32_16x16x32_bf16 v[68:71], v[168:171], v[216:219], v[68:71]
	v_mfma_f32_16x16x32_bf16 v[64:67], v[182:185], v[216:219], v[64:67]
	v_mfma_f32_16x16x32_bf16 v[108:111], v[172:175], v[194:197], v[108:111]
	v_mfma_f32_16x16x32_bf16 v[104:107], v[186:189], v[194:197], v[104:107]
	v_mfma_f32_16x16x32_bf16 v[92:95], v[172:175], v[202:205], v[92:95]
	v_mfma_f32_16x16x32_bf16 v[88:91], v[186:189], v[202:205], v[88:91]
	v_mfma_f32_16x16x32_bf16 v[76:79], v[172:175], v[212:215], v[76:79]
	v_mfma_f32_16x16x32_bf16 v[72:75], v[186:189], v[212:215], v[72:75]
	v_mfma_f32_16x16x32_bf16 v[68:71], v[172:175], v[220:223], v[68:71]
	v_mfma_f32_16x16x32_bf16 v[64:67], v[186:189], v[220:223], v[64:67]
	s_barrier
	s_add_i32 vcc_hi, s42, s83
	v_lshl_add_u64 v[178:179], s[98:99], 0, v[142:143]
	s_mov_b32 m0, vcc_hi
	ds_read_b128 v[190:193], v181 offset:16384
	ds_read_b128 v[194:197], v181 offset:17408
	ds_read_b128 v[198:201], v181 offset:18432
	ds_read_b128 v[202:205], v181 offset:19456
	ds_read_b128 v[206:209], v181 offset:20480
	ds_read_b128 v[212:215], v181 offset:21504
	ds_read_b128 v[216:219], v181 offset:22528
	ds_read_b128 v[220:223], v181 offset:23552
	global_load_lds_dwordx4 v[178:179], off
	s_add_i32 m0, vcc_hi, 0x2000
	v_lshl_add_u64 v[224:225], s[98:99], 0, v[146:147]
	s_add_u32 s98, s98, s18
	s_addc_u32 s99, s99, 0
	s_add_i32 vcc_lo, vcc_lo, s83
	global_load_lds_dwordx4 v[224:225], off
	v_lshl_add_u64 v[226:227], s[98:99], 0, v[142:143]
	s_mov_b32 m0, vcc_lo
	v_lshl_add_u64 v[228:229], s[98:99], 0, v[146:147]
	global_load_lds_dwordx4 v[226:227], off
	s_add_i32 m0, vcc_lo, 0x2000
	v_lshl_add_u64 v[230:231], s[38:39], 0, v[140:141]
	global_load_lds_dwordx4 v[228:229], off
	s_mov_b32 m0, s36
	v_lshl_add_u64 v[232:233], s[38:39], 0, v[144:145]
	global_load_lds_dwordx4 v[230:231], off
	s_mov_b32 m0, s10
	s_nop 0
	global_load_lds_dwordx4 v[232:233], off
	s_waitcnt vmcnt(8)
	s_waitcnt lgkmcnt(0)
	s_barrier
; #define PG8_STAGE(bufoff, gbase, voff) do { _Pragma("unroll") for (int _i = 0; _i < 2; ++_i) \
;         __builtin_amdgcn_global_load_lds((const unsigned*)((const char*)(gbase) + (voff)[_i]), (PG8_LAS unsigned*)(lds + (bufoff) + ldsw + _i * 8192), 16, 0, 0); } while (0)
; #define PG8_LDA(dst, b, h) do { _Pragma("unroll") for (int m = 0; m < 4; ++m) _Pragma("unroll") for (int k = 0; k < 2; ++k) dst[m][k] = *(const PG8_LAS bf16x8*)(lds + PG8_SA(b, h) + aoff + m * 2048 + k * 1024); } while (0)
; #define PG8_LDB(dst, b, h) do { _Pragma("unroll") for (int n = 0; n < 2; ++n) _Pragma("unroll") for (int k = 0; k < 2; ++k) dst[n][k] = *(const PG8_LAS bf16x8*)(lds + PG8_SB(b, h) + boff + n * 2048 + k * 1024); } while (0)
; #define PG8_MMA(ai, bj, At, Bt) do { __builtin_amdgcn_s_setprio(1); _Pragma("unroll") for (int m = 0; m < 4; ++m) _Pragma("unroll") for (int n = 0; n < 2; ++n) _Pragma("unroll") for (int k = 0; k < 2; ++k) \
;         acc[ai][bj][m][n] = __builtin_amdgcn_mfma_f32_16x16x32_bf16(Bt[n][k], At[m][k], acc[ai][bj][m][n], 0, 0, 0); __builtin_amdgcn_s_setprio(0); } while (0)
; #define PG8_WAIT_V(n) asm volatile("s_waitcnt vmcnt(" #n ")" ::: "memory")
; #define PG8_WAIT_L(n) asm volatile("s_waitcnt lgkmcnt(" #n ")" ::: "memory")
; #define PG8_BAR __builtin_amdgcn_s_barrier()
; #define PG8_SCHED __builtin_amdgcn_sched_barrier(0)
;     __device__ __forceinline__ void operator()(const f32x4 (&acc)[2][2][4][2], const Unit& u, int wr, int wc, int fr, int fq) const {
;     ...
;                 for (int m = 0; m < 4; ++m) { const int row = row0 + ai * HALF + m * 16; const float rsv = __builtin_amdgcn_rsqf(rs[row] * (1.0f / 1024.0f) + 1e-6f);
; template <class Epi, class Sched, bool ALIGN_EPI = false, bool SP2 = false>
; __device__ __forceinline__ void gemm_phase(PG8_LAS unsigned char* lds, const Gemm g, const Sched& S, const Epi& E, const int wid_) {
;     ...
;             PG8_WAIT_V(8); PG8_WAIT_L(0); PG8_BAR; PG8_MMA(1, 0, At, B0); PG8_MMA(1, 1, At, B1); PG8_BAR; PG8_SCHED;
;             PG8_LDB(B0, 1, 0); PG8_LDB(B1, 1, 1); PG8_SCHED; PG8_LDA(At, 1, 0); PG8_STAGE(PG8_SA(0, 1), a2 + hstepA, voffA);
;             PG8_WAIT_V(8); PG8_WAIT_L(0); PG8_BAR; PG8_MMA(0, 0, At, B0); PG8_MMA(0, 1, At, B1); PG8_BAR; PG8_SCHED;
	s_waitcnt lgkmcnt(0)
	v_mfma_f32_16x16x32_bf16 v[60:63], v[128:131], v[190:193], v[60:63]
	v_mfma_f32_16x16x32_bf16 v[56:59], v[136:139], v[190:193], v[56:59]
	v_mfma_f32_16x16x32_bf16 v[52:55], v[128:131], v[198:201], v[52:55]
	v_mfma_f32_16x16x32_bf16 v[48:51], v[136:139], v[198:201], v[48:51]
	v_mfma_f32_16x16x32_bf16 v[36:39], v[128:131], v[206:209], v[36:39]
	v_mfma_f32_16x16x32_bf16 v[32:35], v[136:139], v[206:209], v[32:35]
	v_mfma_f32_16x16x32_bf16 v[20:23], v[128:131], v[216:219], v[20:23]
	v_mfma_f32_16x16x32_bf16 v[16:19], v[136:139], v[216:219], v[16:19]
	v_mfma_f32_16x16x32_bf16 v[60:63], v[132:135], v[194:197], v[60:63]
	v_mfma_f32_16x16x32_bf16 v[56:59], v[164:167], v[194:197], v[56:59]
	v_mfma_f32_16x16x32_bf16 v[52:55], v[132:135], v[202:205], v[52:55]
	v_mfma_f32_16x16x32_bf16 v[48:51], v[164:167], v[202:205], v[48:51]
	v_mfma_f32_16x16x32_bf16 v[36:39], v[132:135], v[212:215], v[36:39]
	v_mfma_f32_16x16x32_bf16 v[32:35], v[164:167], v[212:215], v[32:35]
	v_mfma_f32_16x16x32_bf16 v[20:23], v[132:135], v[220:223], v[20:23]
	v_mfma_f32_16x16x32_bf16 v[16:19], v[164:167], v[220:223], v[16:19]
	v_mfma_f32_16x16x32_bf16 v[44:47], v[168:171], v[190:193], v[44:47]
	v_mfma_f32_16x16x32_bf16 v[40:43], v[182:185], v[190:193], v[40:43]
	v_mfma_f32_16x16x32_bf16 v[28:31], v[168:171], v[198:201], v[28:31]
	v_mfma_f32_16x16x32_bf16 v[24:27], v[182:185], v[198:201], v[24:27]
	v_mfma_f32_16x16x32_bf16 v[12:15], v[168:171], v[206:209], v[12:15]
	v_mfma_f32_16x16x32_bf16 v[8:11], v[182:185], v[206:209], v[8:11]
	v_mfma_f32_16x16x32_bf16 v[4:7], v[168:171], v[216:219], v[4:7]
	v_mfma_f32_16x16x32_bf16 v[0:3], v[182:185], v[216:219], v[0:3]
	v_mfma_f32_16x16x32_bf16 v[44:47], v[172:175], v[194:197], v[44:47]
	v_mfma_f32_16x16x32_bf16 v[40:43], v[186:189], v[194:197], v[40:43]
	v_mfma_f32_16x16x32_bf16 v[28:31], v[172:175], v[202:205], v[28:31]
	v_mfma_f32_16x16x32_bf16 v[24:27], v[186:189], v[202:205], v[24:27]
	v_mfma_f32_16x16x32_bf16 v[12:15], v[172:175], v[212:215], v[12:15]
	v_mfma_f32_16x16x32_bf16 v[8:11], v[186:189], v[212:215], v[8:11]
	v_mfma_f32_16x16x32_bf16 v[4:7], v[172:175], v[220:223], v[4:7]
	v_mfma_f32_16x16x32_bf16 v[0:3], v[186:189], v[220:223], v[0:3]
	s_barrier
	s_add_i32 s98, 0, 0x18000
	s_add_i32 s99, 0, 0x1c000
	v_add_u32_e32 v164, s98, v180
	v_add_u32_e32 v176, s99, v180
	ds_read_b128 v[128:131], v164
	ds_read_b128 v[132:135], v164 offset:1024
	ds_read_b128 v[136:139], v164 offset:2048
	ds_read_b128 v[164:167], v164 offset:3072
	ds_read_b128 v[168:171], v176
	ds_read_b128 v[172:175], v176 offset:1024
	ds_read_b128 v[182:185], v176 offset:2048
	ds_read_b128 v[186:189], v176 offset:3072
	s_add_u32 s38, s38, s88
	s_addc_u32 s39, s39, 0
	s_mov_b32 m0, s11
	v_lshl_add_u64 v[234:235], s[38:39], 0, v[140:141]
	ds_read_b128 v[190:193], v181 offset:32768
	ds_read_b128 v[194:197], v181 offset:33792
	ds_read_b128 v[198:201], v181 offset:34816
	ds_read_b128 v[202:205], v181 offset:35840
	ds_read_b128 v[206:209], v181 offset:36864
	ds_read_b128 v[212:215], v181 offset:37888
	ds_read_b128 v[216:219], v181 offset:38912
	ds_read_b128 v[220:223], v181 offset:39936
	global_load_lds_dwordx4 v[234:235], off
	v_lshl_add_u64 v[234:235], s[38:39], 0, v[144:145]
	s_mov_b32 m0, s55
	s_nop 0
	global_load_lds_dwordx4 v[234:235], off
	s_waitcnt vmcnt(8)
	s_waitcnt lgkmcnt(0)
	s_barrier
	s_waitcnt lgkmcnt(0)
	s_cmp_ge_u32 s97, s71
	s_cbranch_scc0 .Lrs_skip
	v_lshl_add_u32 v255, s48, 8, v153
	v_lshlrev_b32_e32 v255, 2, v255
	global_load_dword v246, v255, s[26:27]
	global_load_dword v247, v255, s[26:27] offset:64
	global_load_dword v248, v255, s[26:27] offset:128
	global_load_dword v249, v255, s[26:27] offset:192
	global_load_dword v250, v255, s[26:27] offset:512
	global_load_dword v252, v255, s[26:27] offset:576
	global_load_dword v253, v255, s[26:27] offset:640
	global_load_dword v255, v255, s[26:27] offset:704
; #define PG8_STAGE(bufoff, gbase, voff) do { _Pragma("unroll") for (int _i = 0; _i < 2; ++_i) \
;         __builtin_amdgcn_global_load_lds((const unsigned*)((const char*)(gbase) + (voff)[_i]), (PG8_LAS unsigned*)(lds + (bufoff) + ldsw + _i * 8192), 16, 0, 0); } while (0)
; #define PG8_LDA(dst, b, h) do { _Pragma("unroll") for (int m = 0; m < 4; ++m) _Pragma("unroll") for (int k = 0; k < 2; ++k) dst[m][k] = *(const PG8_LAS bf16x8*)(lds + PG8_SA(b, h) + aoff + m * 2048 + k * 1024); } while (0)
; #define PG8_MMA(ai, bj, At, Bt) do { __builtin_amdgcn_s_setprio(1); _Pragma("unroll") for (int m = 0; m < 4; ++m) _Pragma("unroll") for (int n = 0; n < 2; ++n) _Pragma("unroll") for (int k = 0; k < 2; ++k) \
;         acc[ai][bj][m][n] = __builtin_amdgcn_mfma_f32_16x16x32_bf16(Bt[n][k], At[m][k], acc[ai][bj][m][n], 0, 0, 0); __builtin_amdgcn_s_setprio(0); } while (0)
; #define PG8_WAIT_V(n) asm volatile("s_waitcnt vmcnt(" #n ")" ::: "memory")
; #define PG8_WAIT_L(n) asm volatile("s_waitcnt lgkmcnt(" #n ")" ::: "memory")
; #define PG8_BAR __builtin_amdgcn_s_barrier()
; #define PG8_SCHED __builtin_amdgcn_sched_barrier(0)
; template <class Epi, class Sched, bool ALIGN_EPI = false, bool SP2 = false>
; __device__ __forceinline__ void gemm_phase(PG8_LAS unsigned char* lds, const Gemm g, const Sched& S, const Epi& E, const int wid_) {
;     ...
;             PG8_WAIT_V(8); PG8_WAIT_L(0); PG8_BAR; PG8_MMA(0, 0, At, B0); PG8_MMA(0, 1, At, B1); PG8_BAR; PG8_SCHED;
;             PG8_LDA(At, 1, 1); PG8_STAGE(PG8_SB(1, 0), b3, voffB); PG8_STAGE(PG8_SB(1, 1), b3 + hstepB, voffB); PG8_STAGE(PG8_SA(1, 0), a3, voffA);
;             PG8_WAIT_V(8); PG8_WAIT_L(0); PG8_BAR; PG8_MMA(1, 0, At, B0); PG8_MMA(1, 1, At, B1); PG8_BAR; PG8_SCHED;
;     ...
;         if constexpr (ALIGN_EPI) { if (wr == 0) PG8_BAR; }
;         if constexpr (!Epi::AFTER_DRAIN) { E(acc, cur, wr, wc, fr, fq); S.done(cur); }
.Lrs_skip:
	v_mfma_f32_16x16x32_bf16 v[124:127], v[128:131], v[190:193], v[124:127]
	v_mfma_f32_16x16x32_bf16 v[120:123], v[136:139], v[190:193], v[120:123]
	v_mfma_f32_16x16x32_bf16 v[116:119], v[128:131], v[198:201], v[116:119]
	v_mfma_f32_16x16x32_bf16 v[112:115], v[136:139], v[198:201], v[112:115]
	v_mfma_f32_16x16x32_bf16 v[100:103], v[128:131], v[206:209], v[100:103]
	v_mfma_f32_16x16x32_bf16 v[96:99], v[136:139], v[206:209], v[96:99]
	v_mfma_f32_16x16x32_bf16 v[84:87], v[128:131], v[216:219], v[84:87]
	v_mfma_f32_16x16x32_bf16 v[80:83], v[136:139], v[216:219], v[80:83]
	v_mfma_f32_16x16x32_bf16 v[124:127], v[132:135], v[194:197], v[124:127]
	v_mfma_f32_16x16x32_bf16 v[120:123], v[164:167], v[194:197], v[120:123]
	v_mfma_f32_16x16x32_bf16 v[116:119], v[132:135], v[202:205], v[116:119]
	v_mfma_f32_16x16x32_bf16 v[112:115], v[164:167], v[202:205], v[112:115]
	v_mfma_f32_16x16x32_bf16 v[100:103], v[132:135], v[212:215], v[100:103]
	v_mfma_f32_16x16x32_bf16 v[96:99], v[164:167], v[212:215], v[96:99]
	v_mfma_f32_16x16x32_bf16 v[84:87], v[132:135], v[220:223], v[84:87]
	v_mfma_f32_16x16x32_bf16 v[80:83], v[164:167], v[220:223], v[80:83]
	v_mfma_f32_16x16x32_bf16 v[108:111], v[168:171], v[190:193], v[108:111]
	v_mfma_f32_16x16x32_bf16 v[104:107], v[182:185], v[190:193], v[104:107]
	v_mfma_f32_16x16x32_bf16 v[92:95], v[168:171], v[198:201], v[92:95]
	v_mfma_f32_16x16x32_bf16 v[88:91], v[182:185], v[198:201], v[88:91]
	v_mfma_f32_16x16x32_bf16 v[76:79], v[168:171], v[206:209], v[76:79]
	v_mfma_f32_16x16x32_bf16 v[72:75], v[182:185], v[206:209], v[72:75]
	v_mfma_f32_16x16x32_bf16 v[68:71], v[168:171], v[216:219], v[68:71]
	v_mfma_f32_16x16x32_bf16 v[64:67], v[182:185], v[216:219], v[64:67]
	v_mfma_f32_16x16x32_bf16 v[108:111], v[172:175], v[194:197], v[108:111]
	v_mfma_f32_16x16x32_bf16 v[104:107], v[186:189], v[194:197], v[104:107]
	v_mfma_f32_16x16x32_bf16 v[92:95], v[172:175], v[202:205], v[92:95]
	v_mfma_f32_16x16x32_bf16 v[88:91], v[186:189], v[202:205], v[88:91]
	v_mfma_f32_16x16x32_bf16 v[76:79], v[172:175], v[212:215], v[76:79]
	v_mfma_f32_16x16x32_bf16 v[72:75], v[186:189], v[212:215], v[72:75]
	v_mfma_f32_16x16x32_bf16 v[68:71], v[172:175], v[220:223], v[68:71]
	v_mfma_f32_16x16x32_bf16 v[64:67], v[186:189], v[220:223], v[64:67]
	s_barrier
	s_add_i32 s38, s98, s83
	v_lshl_add_u64 v[178:179], v[178:179], 0, s[66:67]
	s_mov_b32 m0, s38
	ds_read_b128 v[190:193], v181 offset:49152
	ds_read_b128 v[194:197], v181 offset:50176
	ds_read_b128 v[198:201], v181 offset:51200
	ds_read_b128 v[202:205], v181 offset:52224
	ds_read_b128 v[206:209], v181 offset:53248
	ds_read_b128 v[212:215], v181 offset:54272
	ds_read_b128 v[216:219], v181 offset:55296
	ds_read_b128 v[220:223], v181 offset:56320
	global_load_lds_dwordx4 v[178:179], off
	v_lshl_add_u64 v[178:179], v[224:225], 0, s[66:67]
	s_add_i32 m0, s38, 0x2000
	s_add_i32 s38, s99, s83
	global_load_lds_dwordx4 v[178:179], off
	v_lshl_add_u64 v[178:179], v[226:227], 0, s[66:67]
	s_mov_b32 m0, s38
	s_nop 0
	global_load_lds_dwordx4 v[178:179], off
	v_lshl_add_u64 v[178:179], v[228:229], 0, s[66:67]
	s_add_i32 m0, s38, 0x2000
	s_nop 0
	global_load_lds_dwordx4 v[178:179], off
	v_lshl_add_u64 v[178:179], v[230:231], 0, s[66:67]
	s_mov_b32 m0, s33
	s_nop 0
	global_load_lds_dwordx4 v[178:179], off
	v_lshl_add_u64 v[178:179], v[232:233], 0, s[66:67]
	s_mov_b32 m0, s52
	s_nop 0
	global_load_lds_dwordx4 v[178:179], off
	s_waitcnt vmcnt(8)
	s_waitcnt lgkmcnt(0)
	s_barrier
	s_waitcnt lgkmcnt(0)
	v_mfma_f32_16x16x32_bf16 v[60:63], v[128:131], v[190:193], v[60:63]
	v_mfma_f32_16x16x32_bf16 v[56:59], v[136:139], v[190:193], v[56:59]
	v_mfma_f32_16x16x32_bf16 v[52:55], v[128:131], v[198:201], v[52:55]
	v_mfma_f32_16x16x32_bf16 v[48:51], v[136:139], v[198:201], v[48:51]
	v_mfma_f32_16x16x32_bf16 v[36:39], v[128:131], v[206:209], v[36:39]
	v_mfma_f32_16x16x32_bf16 v[32:35], v[136:139], v[206:209], v[32:35]
	v_mfma_f32_16x16x32_bf16 v[20:23], v[128:131], v[216:219], v[20:23]
	v_mfma_f32_16x16x32_bf16 v[16:19], v[136:139], v[216:219], v[16:19]
	v_mfma_f32_16x16x32_bf16 v[60:63], v[132:135], v[194:197], v[60:63]
	v_mfma_f32_16x16x32_bf16 v[56:59], v[164:167], v[194:197], v[56:59]
	v_mfma_f32_16x16x32_bf16 v[52:55], v[132:135], v[202:205], v[52:55]
	v_mfma_f32_16x16x32_bf16 v[48:51], v[164:167], v[202:205], v[48:51]
	v_mfma_f32_16x16x32_bf16 v[36:39], v[132:135], v[212:215], v[36:39]
	v_mfma_f32_16x16x32_bf16 v[32:35], v[164:167], v[212:215], v[32:35]
	v_mfma_f32_16x16x32_bf16 v[20:23], v[132:135], v[220:223], v[20:23]
	v_mfma_f32_16x16x32_bf16 v[16:19], v[164:167], v[220:223], v[16:19]
	v_mfma_f32_16x16x32_bf16 v[44:47], v[168:171], v[190:193], v[44:47]
	v_mfma_f32_16x16x32_bf16 v[40:43], v[182:185], v[190:193], v[40:43]
	v_mfma_f32_16x16x32_bf16 v[28:31], v[168:171], v[198:201], v[28:31]
	v_mfma_f32_16x16x32_bf16 v[24:27], v[182:185], v[198:201], v[24:27]
	v_mfma_f32_16x16x32_bf16 v[12:15], v[168:171], v[206:209], v[12:15]
	v_mfma_f32_16x16x32_bf16 v[8:11], v[182:185], v[206:209], v[8:11]
	v_mfma_f32_16x16x32_bf16 v[4:7], v[168:171], v[216:219], v[4:7]
	v_mfma_f32_16x16x32_bf16 v[0:3], v[182:185], v[216:219], v[0:3]
	v_mfma_f32_16x16x32_bf16 v[44:47], v[172:175], v[194:197], v[44:47]
	v_mfma_f32_16x16x32_bf16 v[40:43], v[186:189], v[194:197], v[40:43]
	v_mfma_f32_16x16x32_bf16 v[28:31], v[172:175], v[202:205], v[28:31]
	v_mfma_f32_16x16x32_bf16 v[24:27], v[186:189], v[202:205], v[24:27]
	v_mfma_f32_16x16x32_bf16 v[12:15], v[172:175], v[212:215], v[12:15]
	v_mfma_f32_16x16x32_bf16 v[8:11], v[186:189], v[212:215], v[8:11]
	v_mfma_f32_16x16x32_bf16 v[4:7], v[172:175], v[220:223], v[4:7]
	v_mfma_f32_16x16x32_bf16 v[0:3], v[186:189], v[220:223], v[0:3]
	s_barrier
	s_add_u32 s49, s49, 0x100
	s_addc_u32 s62, s62, 0
	s_add_u32 s6, s6, 0x100
	s_addc_u32 s7, s7, 0
	s_cmp_ge_u32 s97, s71
	s_mov_b32 s38, s97
	s_cbranch_scc0 .LBB0_380
	s_setprio 0
	s_and_b64 vcc, exec, s[94:95]
	s_cbranch_vccz .LBB0_384
	s_barrier
	v_lshl_add_u32 v164, s48, 8, v153
	s_cmp_lt_i32 s37, 2
	s_mov_b64 s[6:7], -1
	s_cbranch_scc0 .LBB0_385

; __device__ __forceinline__ float sigm_f(float v) { return __builtin_amdgcn_rcpf(1.0f + __builtin_amdgcn_exp2f(-1.44269504f * v)); }
; __device__ __forceinline__ float silu_f(float v) { return v * sigm_f(v); }
;     __device__ __forceinline__ void operator()(const f32x4 (&acc)[2][2][4][2], const Unit& u, int wr, int wc, int fr, int fq) const {
;     ...
;                 for (int ai = 0; ai < 2; ++ai)
; #pragma unroll
;                     for (int m = 0; m < 4; ++m) { const int row = row0 + ai * HALF + m * 16; const float rsv = __builtin_amdgcn_rsqf(rs[row] * (1.0f / 1024.0f) + 1e-6f);
;                         bf16_t* rowp = O + (size_t)row * ldc + u.pn * BM + cw;
; #pragma unroll
;                         for (int bj = 0; bj < 2; ++bj) { f32x4 v0 = acc[ai][bj][m][0] * rsv, v1 = acc[ai][bj][m][1] * rsv;
;                             if (sub == 1) {
; #pragma unroll
;                                 for (int e = 0; e < 4; ++e) { v0[e] = silu_f(v0[e]); v1[e] = silu_f(v1[e]); } }
;                             else if (sub == 3) {
; #pragma unroll
;                                 for (int e = 0; e < 4; ++e) { v0[e] = sigm_f(v0[e]); v1[e] = sigm_f(v1[e]); } }
.LBB0_486:
	s_andn2_b64 vcc, exec, s[6:7]
	s_cbranch_vccnz .LBB0_587
	v_ashrrev_i32_e32 v165, 31, v164
	v_lshl_add_u64 v[128:129], v[164:165], 2, s[26:27]
	s_lshl_b32 s62, s40, 8
	s_cmp_lt_i32 s40, 4
	s_mov_b64 s[6:7], -1
	s_waitcnt vmcnt(6) lgkmcnt(0)
	v_fmamk_f32 v130, v246, 0x3a800000, v237
	v_rsq_f32_e32 v130, v130
	s_cbranch_scc1 .LBB0_585
	s_cmp_lt_u32 s40, 12
	s_cselect_b32 s6, 2, 3
	s_cmp_gt_u32 s40, 7
	s_cselect_b32 s38, s6, 1
	v_pk_mul_f32 v[132:133], v[126:127], v[130:131] op_sel_hi:[1,0]
	v_pk_mul_f32 v[134:135], v[124:125], v[130:131] op_sel_hi:[1,0]
	v_pk_mul_f32 v[136:137], v[122:123], v[130:131] op_sel_hi:[1,0]
	v_pk_mul_f32 v[138:139], v[120:121], v[130:131] op_sel_hi:[1,0]
	s_cmp_gt_i32 s38, 2
	s_mov_b64 s[6:7], -1
	s_cbranch_scc0 .LBB0_490
	v_mul_f32_e32 v131, 0xbfb8aa3b, v134
	v_exp_f32_e32 v131, v131
	v_mul_f32_e32 v165, 0xbfb8aa3b, v138
	v_exp_f32_e32 v165, v165
	v_mul_f32_e32 v167, 0xbfb8aa3b, v139
	v_add_f32_e32 v131, 1.0, v131
	v_exp_f32_e32 v168, v167
	v_add_f32_e32 v166, 1.0, v165
	v_rcp_f32_e32 v165, v131
	v_mul_f32_e32 v131, 0xbfb8aa3b, v135
	v_exp_f32_e32 v131, v131
	v_rcp_f32_e32 v166, v166
	s_mov_b64 s[6:7], 0
	v_add_f32_e32 v131, 1.0, v131
	v_rcp_f32_e32 v167, v131
	v_add_f32_e32 v131, 1.0, v168
	v_mul_f32_e32 v168, 0xbfb8aa3b, v132
	v_exp_f32_e32 v169, v168
	v_mul_f32_e32 v168, 0xbfb8aa3b, v136
	v_exp_f32_e32 v170, v168
	v_rcp_f32_e32 v168, v131
	v_add_f32_e32 v131, 1.0, v169
	v_rcp_f32_e32 v169, v131
	v_add_f32_e32 v131, 1.0, v170
	v_mul_f32_e32 v170, 0xbfb8aa3b, v133
	v_exp_f32_e32 v171, v170
	v_mul_f32_e32 v170, 0xbfb8aa3b, v137
	v_exp_f32_e32 v173, v170
	v_rcp_f32_e32 v170, v131
	v_add_f32_e32 v131, 1.0, v171
	v_rcp_f32_e32 v172, v131
	v_add_f32_e32 v131, 1.0, v173
	v_rcp_f32_e32 v171, v131

; __device__ __forceinline__ float silu_f(float v) { return v * sigm_f(v); }
;     __device__ __forceinline__ void operator()(const f32x4 (&acc)[2][2][4][2], const Unit& u, int wr, int wc, int fr, int fq) const {
;     ...
;         } else if (mode == M_SWIGLU) {
; #pragma unroll
;             for (int ai = 0; ai < 2; ++ai)
; #pragma unroll
;                 for (int m = 0; m < 4; ++m) { const int row = row0 + ai * HALF + m * 16; const float rsv = __builtin_amdgcn_rsqf(rs[row] * (1.0f / 1024.0f) + 1e-6f);
;                     f32x4 h0, h1;
; #pragma unroll
;                     for (int e = 0; e < 4; ++e) { h0[e] = silu_f(acc[ai][0][m][0][e] * rsv) * (acc[ai][1][m][0][e] * rsv); h1[e] = silu_f(acc[ai][0][m][1][e] * rsv) * (acc[ai][1][m][1][e] * rsv); }
;                     store8(O + (size_t)row * ldc + u.pn * HALF + cw, h0, h1); }
.LBB0_588:
	s_mov_b64 s[6:7], -1
	s_cmp_lt_i32 s37, 1
	v_lshlrev_b64 v[128:129], 1, v[148:149]
	v_or_b32_e32 v171, 16, v164
	v_or_b32_e32 v170, 32, v164
	v_or_b32_e32 v169, 48, v164
	v_add_u32_e32 v168, 0x80, v164
	v_add_u32_e32 v167, 0x90, v164
	v_add_u32_e32 v166, 0xa0, v164
	s_cbranch_scc1 .LBB0_590
	v_ashrrev_i32_e32 v165, 31, v164
	v_lshl_add_u64 v[130:131], v[164:165], 2, s[26:27]
	s_lshl_b32 s6, s40, 7
	s_ashr_i32 s7, s6, 31
	s_lshl_b64 s[6:7], s[6:7], 1
	v_add_u32_e32 v165, 0xb0, v164
	s_waitcnt vmcnt(6) lgkmcnt(0)
	v_mov_b32_e32 v188, 1.0
	v_mov_b32_e32 v189, 1.0
	v_fmamk_f32 v206, v246, 0x3a800000, v237
	v_rsq_f32_e32 v182, v206
	v_mad_i64_i32 v[172:173], s[38:39], s82, v164, 0
	v_lshl_add_u64 v[172:173], v[172:173], 1, s[84:85]
	v_lshl_add_u64 v[172:173], v[172:173], 0, s[6:7]
	v_lshl_add_u64 v[172:173], v[172:173], 0, v[128:129]
	v_mul_f32_e32 v184, 0xbfb8aa3b, v182
	v_mul_f32_e32 v186, v182, v182
	v_pk_mul_f32 v[190:191], v[124:125], v[184:185] op_sel_hi:[1,0]
	v_pk_mul_f32 v[192:193], v[126:127], v[184:185] op_sel_hi:[1,0]
	v_pk_mul_f32 v[194:195], v[120:121], v[184:185] op_sel_hi:[1,0]
	v_pk_mul_f32 v[196:197], v[122:123], v[184:185] op_sel_hi:[1,0]
	v_exp_f32_e32 v190, v190
	v_exp_f32_e32 v191, v191
	v_exp_f32_e32 v192, v192
	v_exp_f32_e32 v193, v193
	v_exp_f32_e32 v194, v194
	v_exp_f32_e32 v195, v195
	v_exp_f32_e32 v196, v196
	v_exp_f32_e32 v197, v197
	v_pk_mul_f32 v[198:199], v[124:125], v[108:109]
	v_pk_mul_f32 v[200:201], v[126:127], v[110:111]
	v_pk_mul_f32 v[202:203], v[120:121], v[104:105]
	v_pk_mul_f32 v[204:205], v[122:123], v[106:107]
	v_pk_add_f32 v[190:191], v[190:191], v[188:189]
	v_pk_add_f32 v[192:193], v[192:193], v[188:189]
	v_pk_add_f32 v[194:195], v[194:195], v[188:189]
	v_pk_add_f32 v[196:197], v[196:197], v[188:189]
	v_rcp_f32_e32 v190, v190
	v_rcp_f32_e32 v191, v191
	v_rcp_f32_e32 v192, v192
	v_rcp_f32_e32 v193, v193
	v_rcp_f32_e32 v194, v194
	v_rcp_f32_e32 v195, v195
	v_rcp_f32_e32 v196, v196
	v_rcp_f32_e32 v197, v197
	v_pk_mul_f32 v[198:199], v[198:199], v[186:187] op_sel_hi:[1,0]
	v_pk_mul_f32 v[200:201], v[200:201], v[186:187] op_sel_hi:[1,0]
	v_pk_mul_f32 v[202:203], v[202:203], v[186:187] op_sel_hi:[1,0]
	v_pk_mul_f32 v[204:205], v[204:205], v[186:187] op_sel_hi:[1,0]
	v_pk_mul_f32 v[198:199], v[198:199], v[190:191]
	v_pk_mul_f32 v[200:201], v[200:201], v[192:193]
	v_pk_mul_f32 v[202:203], v[202:203], v[194:195]
	v_pk_mul_f32 v[204:205], v[204:205], v[196:197]
	v_cvt_pk_bf16_f32 v132, v198, v199
	v_cvt_pk_bf16_f32 v133, v200, v201
	v_cvt_pk_bf16_f32 v134, v202, v203
	v_cvt_pk_bf16_f32 v135, v204, v205
	flat_store_dwordx4 v[172:173], v[132:135]
	v_fmamk_f32 v206, v247, 0x3a800000, v237
	v_rsq_f32_e32 v182, v206
	v_mad_i64_i32 v[172:173], s[38:39], s82, v171, 0
	v_lshl_add_u64 v[172:173], v[172:173], 1, s[84:85]
	v_lshl_add_u64 v[172:173], v[172:173], 0, s[6:7]
	v_lshl_add_u64 v[172:173], v[172:173], 0, v[128:129]
	v_mul_f32_e32 v184, 0xbfb8aa3b, v182
	v_mul_f32_e32 v186, v182, v182
	v_pk_mul_f32 v[190:191], v[116:117], v[184:185] op_sel_hi:[1,0]
	v_pk_mul_f32 v[192:193], v[118:119], v[184:185] op_sel_hi:[1,0]
	v_pk_mul_f32 v[194:195], v[112:113], v[184:185] op_sel_hi:[1,0]
	v_pk_mul_f32 v[196:197], v[114:115], v[184:185] op_sel_hi:[1,0]
	v_exp_f32_e32 v190, v190
	v_exp_f32_e32 v191, v191
	v_exp_f32_e32 v192, v192
	v_exp_f32_e32 v193, v193
	v_exp_f32_e32 v194, v194
	v_exp_f32_e32 v195, v195
	v_exp_f32_e32 v196, v196
	v_exp_f32_e32 v197, v197
	v_pk_mul_f32 v[198:199], v[116:117], v[92:93]
	v_pk_mul_f32 v[200:201], v[118:119], v[94:95]
	v_pk_mul_f32 v[202:203], v[112:113], v[88:89]
	v_pk_mul_f32 v[204:205], v[114:115], v[90:91]
	v_pk_add_f32 v[190:191], v[190:191], v[188:189]
	v_pk_add_f32 v[192:193], v[192:193], v[188:189]
	v_pk_add_f32 v[194:195], v[194:195], v[188:189]
	v_pk_add_f32 v[196:197], v[196:197], v[188:189]
	v_rcp_f32_e32 v190, v190
	v_rcp_f32_e32 v191, v191
	v_rcp_f32_e32 v192, v192
	v_rcp_f32_e32 v193, v193
	v_rcp_f32_e32 v194, v194
	v_rcp_f32_e32 v195, v195
	v_rcp_f32_e32 v196, v196
	v_rcp_f32_e32 v197, v197
	v_pk_mul_f32 v[198:199], v[198:199], v[186:187] op_sel_hi:[1,0]
	v_pk_mul_f32 v[200:201], v[200:201], v[186:187] op_sel_hi:[1,0]
	v_pk_mul_f32 v[202:203], v[202:203], v[186:187] op_sel_hi:[1,0]
	v_pk_mul_f32 v[204:205], v[204:205], v[186:187] op_sel_hi:[1,0]
	v_pk_mul_f32 v[198:199], v[198:199], v[190:191]
	v_pk_mul_f32 v[200:201], v[200:201], v[192:193]
	v_pk_mul_f32 v[202:203], v[202:203], v[194:195]
	v_pk_mul_f32 v[204:205], v[204:205], v[196:197]
	v_cvt_pk_bf16_f32 v132, v198, v199
	v_cvt_pk_bf16_f32 v133, v200, v201
	v_cvt_pk_bf16_f32 v134, v202, v203
	v_cvt_pk_bf16_f32 v135, v204, v205
	flat_store_dwordx4 v[172:173], v[132:135]
	v_fmamk_f32 v206, v248, 0x3a800000, v237
	v_rsq_f32_e32 v182, v206
	v_mad_i64_i32 v[172:173], s[38:39], s82, v170, 0
	v_lshl_add_u64 v[172:173], v[172:173], 1, s[84:85]
	v_lshl_add_u64 v[172:173], v[172:173], 0, s[6:7]
	v_lshl_add_u64 v[172:173], v[172:173], 0, v[128:129]
	v_mul_f32_e32 v184, 0xbfb8aa3b, v182
	v_mul_f32_e32 v186, v182, v182
	v_pk_mul_f32 v[190:191], v[100:101], v[184:185] op_sel_hi:[1,0]
	v_pk_mul_f32 v[192:193], v[102:103], v[184:185] op_sel_hi:[1,0]
	v_pk_mul_f32 v[194:195], v[96:97], v[184:185] op_sel_hi:[1,0]
	v_pk_mul_f32 v[196:197], v[98:99], v[184:185] op_sel_hi:[1,0]
	v_exp_f32_e32 v190, v190
	v_exp_f32_e32 v191, v191
	v_exp_f32_e32 v192, v192
	v_exp_f32_e32 v193, v193
	v_exp_f32_e32 v194, v194
	v_exp_f32_e32 v195, v195
	v_exp_f32_e32 v196, v196
	v_exp_f32_e32 v197, v197
	v_pk_mul_f32 v[198:199], v[100:101], v[76:77]
	v_pk_mul_f32 v[200:201], v[102:103], v[78:79]
	v_pk_mul_f32 v[202:203], v[96:97], v[72:73]
; __device__ __forceinline__ float silu_f(float v) { return v * sigm_f(v); }
;     __device__ __forceinline__ void operator()(const f32x4 (&acc)[2][2][4][2], const Unit& u, int wr, int wc, int fr, int fq) const {
;     ...
;                 for (int m = 0; m < 4; ++m) { const int row = row0 + ai * HALF + m * 16; const float rsv = __builtin_amdgcn_rsqf(rs[row] * (1.0f / 1024.0f) + 1e-6f);
;                     f32x4 h0, h1;
; #pragma unroll
;                     for (int e = 0; e < 4; ++e) { h0[e] = silu_f(acc[ai][0][m][0][e] * rsv) * (acc[ai][1][m][0][e] * rsv); h1[e] = silu_f(acc[ai][0][m][1][e] * rsv) * (acc[ai][1][m][1][e] * rsv); }
;                     store8(O + (size_t)row * ldc + u.pn * HALF + cw, h0, h1); }
	v_pk_mul_f32 v[204:205], v[98:99], v[74:75]
	v_pk_add_f32 v[190:191], v[190:191], v[188:189]
	v_pk_add_f32 v[192:193], v[192:193], v[188:189]
	v_pk_add_f32 v[194:195], v[194:195], v[188:189]
	v_pk_add_f32 v[196:197], v[196:197], v[188:189]
	v_rcp_f32_e32 v190, v190
	v_rcp_f32_e32 v191, v191
	v_rcp_f32_e32 v192, v192
	v_rcp_f32_e32 v193, v193
	v_rcp_f32_e32 v194, v194
	v_rcp_f32_e32 v195, v195
	v_rcp_f32_e32 v196, v196
	v_rcp_f32_e32 v197, v197
	v_pk_mul_f32 v[198:199], v[198:199], v[186:187] op_sel_hi:[1,0]
	v_pk_mul_f32 v[200:201], v[200:201], v[186:187] op_sel_hi:[1,0]
	v_pk_mul_f32 v[202:203], v[202:203], v[186:187] op_sel_hi:[1,0]
	v_pk_mul_f32 v[204:205], v[204:205], v[186:187] op_sel_hi:[1,0]
	v_pk_mul_f32 v[198:199], v[198:199], v[190:191]
	v_pk_mul_f32 v[200:201], v[200:201], v[192:193]
	v_pk_mul_f32 v[202:203], v[202:203], v[194:195]
	v_pk_mul_f32 v[204:205], v[204:205], v[196:197]
	v_cvt_pk_bf16_f32 v132, v198, v199
	v_cvt_pk_bf16_f32 v133, v200, v201
	v_cvt_pk_bf16_f32 v134, v202, v203
	v_cvt_pk_bf16_f32 v135, v204, v205
	flat_store_dwordx4 v[172:173], v[132:135]
	v_fmamk_f32 v206, v249, 0x3a800000, v237
	v_rsq_f32_e32 v182, v206
	v_mad_i64_i32 v[172:173], s[38:39], s82, v169, 0
	v_lshl_add_u64 v[172:173], v[172:173], 1, s[84:85]
	v_lshl_add_u64 v[172:173], v[172:173], 0, s[6:7]
	v_lshl_add_u64 v[172:173], v[172:173], 0, v[128:129]
	v_mul_f32_e32 v184, 0xbfb8aa3b, v182
	v_mul_f32_e32 v186, v182, v182
	v_pk_mul_f32 v[190:191], v[84:85], v[184:185] op_sel_hi:[1,0]
	v_pk_mul_f32 v[192:193], v[86:87], v[184:185] op_sel_hi:[1,0]
	v_pk_mul_f32 v[194:195], v[80:81], v[184:185] op_sel_hi:[1,0]
	v_pk_mul_f32 v[196:197], v[82:83], v[184:185] op_sel_hi:[1,0]
	v_exp_f32_e32 v190, v190
	v_exp_f32_e32 v191, v191
	v_exp_f32_e32 v192, v192
	v_exp_f32_e32 v193, v193
	v_exp_f32_e32 v194, v194
	v_exp_f32_e32 v195, v195
	v_exp_f32_e32 v196, v196
	v_exp_f32_e32 v197, v197
	v_pk_mul_f32 v[198:199], v[84:85], v[68:69]
	v_pk_mul_f32 v[200:201], v[86:87], v[70:71]
	v_pk_mul_f32 v[202:203], v[80:81], v[64:65]
	v_pk_mul_f32 v[204:205], v[82:83], v[66:67]
	v_pk_add_f32 v[190:191], v[190:191], v[188:189]
	v_pk_add_f32 v[192:193], v[192:193], v[188:189]
	v_pk_add_f32 v[194:195], v[194:195], v[188:189]
	v_pk_add_f32 v[196:197], v[196:197], v[188:189]
	v_rcp_f32_e32 v190, v190
	v_rcp_f32_e32 v191, v191
	v_rcp_f32_e32 v192, v192
	v_rcp_f32_e32 v193, v193
	v_rcp_f32_e32 v194, v194
	v_rcp_f32_e32 v195, v195
	v_rcp_f32_e32 v196, v196
	v_rcp_f32_e32 v197, v197
	v_pk_mul_f32 v[198:199], v[198:199], v[186:187] op_sel_hi:[1,0]
	v_pk_mul_f32 v[200:201], v[200:201], v[186:187] op_sel_hi:[1,0]
	v_pk_mul_f32 v[202:203], v[202:203], v[186:187] op_sel_hi:[1,0]
	v_pk_mul_f32 v[204:205], v[204:205], v[186:187] op_sel_hi:[1,0]
	v_pk_mul_f32 v[198:199], v[198:199], v[190:191]
	v_pk_mul_f32 v[200:201], v[200:201], v[192:193]
	v_pk_mul_f32 v[202:203], v[202:203], v[194:195]
	v_pk_mul_f32 v[204:205], v[204:205], v[196:197]
	v_cvt_pk_bf16_f32 v132, v198, v199
	v_cvt_pk_bf16_f32 v133, v200, v201
	v_cvt_pk_bf16_f32 v134, v202, v203
	v_cvt_pk_bf16_f32 v135, v204, v205
	flat_store_dwordx4 v[172:173], v[132:135]
	v_fmamk_f32 v206, v250, 0x3a800000, v237
	v_rsq_f32_e32 v182, v206
	v_mad_i64_i32 v[172:173], s[38:39], s82, v168, 0
	v_lshl_add_u64 v[172:173], v[172:173], 1, s[84:85]
	v_lshl_add_u64 v[172:173], v[172:173], 0, s[6:7]
	v_lshl_add_u64 v[172:173], v[172:173], 0, v[128:129]
	v_mul_f32_e32 v184, 0xbfb8aa3b, v182
	v_mul_f32_e32 v186, v182, v182
	v_pk_mul_f32 v[190:191], v[60:61], v[184:185] op_sel_hi:[1,0]
	v_pk_mul_f32 v[192:193], v[62:63], v[184:185] op_sel_hi:[1,0]
	v_pk_mul_f32 v[194:195], v[56:57], v[184:185] op_sel_hi:[1,0]
	v_pk_mul_f32 v[196:197], v[58:59], v[184:185] op_sel_hi:[1,0]
	v_exp_f32_e32 v190, v190
	v_exp_f32_e32 v191, v191
	v_exp_f32_e32 v192, v192
	v_exp_f32_e32 v193, v193
	v_exp_f32_e32 v194, v194
	v_exp_f32_e32 v195, v195
	v_exp_f32_e32 v196, v196
	v_exp_f32_e32 v197, v197
	v_pk_mul_f32 v[198:199], v[60:61], v[44:45]
	v_pk_mul_f32 v[200:201], v[62:63], v[46:47]
	v_pk_mul_f32 v[202:203], v[56:57], v[40:41]
	v_pk_mul_f32 v[204:205], v[58:59], v[42:43]
	v_pk_add_f32 v[190:191], v[190:191], v[188:189]
	v_pk_add_f32 v[192:193], v[192:193], v[188:189]
	v_pk_add_f32 v[194:195], v[194:195], v[188:189]
	v_pk_add_f32 v[196:197], v[196:197], v[188:189]
	v_rcp_f32_e32 v190, v190
	v_rcp_f32_e32 v191, v191
	v_rcp_f32_e32 v192, v192
	v_rcp_f32_e32 v193, v193
	v_rcp_f32_e32 v194, v194
	v_rcp_f32_e32 v195, v195
	v_rcp_f32_e32 v196, v196
	v_rcp_f32_e32 v197, v197
	v_pk_mul_f32 v[198:199], v[198:199], v[186:187] op_sel_hi:[1,0]
	v_pk_mul_f32 v[200:201], v[200:201], v[186:187] op_sel_hi:[1,0]
	v_pk_mul_f32 v[202:203], v[202:203], v[186:187] op_sel_hi:[1,0]
	v_pk_mul_f32 v[204:205], v[204:205], v[186:187] op_sel_hi:[1,0]
	v_pk_mul_f32 v[198:199], v[198:199], v[190:191]
	v_pk_mul_f32 v[200:201], v[200:201], v[192:193]
	v_pk_mul_f32 v[202:203], v[202:203], v[194:195]
	v_pk_mul_f32 v[204:205], v[204:205], v[196:197]
	v_cvt_pk_bf16_f32 v132, v198, v199
	v_cvt_pk_bf16_f32 v133, v200, v201
	v_cvt_pk_bf16_f32 v134, v202, v203
	v_cvt_pk_bf16_f32 v135, v204, v205
	flat_store_dwordx4 v[172:173], v[132:135]
	v_fmamk_f32 v206, v252, 0x3a800000, v237
	v_rsq_f32_e32 v182, v206
	v_mad_i64_i32 v[172:173], s[38:39], s82, v167, 0
	v_lshl_add_u64 v[172:173], v[172:173], 1, s[84:85]
	v_lshl_add_u64 v[172:173], v[172:173], 0, s[6:7]
	v_lshl_add_u64 v[172:173], v[172:173], 0, v[128:129]
	v_mul_f32_e32 v184, 0xbfb8aa3b, v182
	v_mul_f32_e32 v186, v182, v182
	v_pk_mul_f32 v[190:191], v[52:53], v[184:185] op_sel_hi:[1,0]
	v_pk_mul_f32 v[192:193], v[54:55], v[184:185] op_sel_hi:[1,0]
; __device__ __forceinline__ float silu_f(float v) { return v * sigm_f(v); }
;     __device__ __forceinline__ void operator()(const f32x4 (&acc)[2][2][4][2], const Unit& u, int wr, int wc, int fr, int fq) const {
;     ...
;                 for (int m = 0; m < 4; ++m) { const int row = row0 + ai * HALF + m * 16; const float rsv = __builtin_amdgcn_rsqf(rs[row] * (1.0f / 1024.0f) + 1e-6f);
;                     f32x4 h0, h1;
; #pragma unroll
;                     for (int e = 0; e < 4; ++e) { h0[e] = silu_f(acc[ai][0][m][0][e] * rsv) * (acc[ai][1][m][0][e] * rsv); h1[e] = silu_f(acc[ai][0][m][1][e] * rsv) * (acc[ai][1][m][1][e] * rsv); }
;                     store8(O + (size_t)row * ldc + u.pn * HALF + cw, h0, h1); }
	v_pk_mul_f32 v[194:195], v[48:49], v[184:185] op_sel_hi:[1,0]
	v_pk_mul_f32 v[196:197], v[50:51], v[184:185] op_sel_hi:[1,0]
	v_exp_f32_e32 v190, v190
	v_exp_f32_e32 v191, v191
	v_exp_f32_e32 v192, v192
	v_exp_f32_e32 v193, v193
	v_exp_f32_e32 v194, v194
	v_exp_f32_e32 v195, v195
	v_exp_f32_e32 v196, v196
	v_exp_f32_e32 v197, v197
	v_pk_mul_f32 v[198:199], v[52:53], v[28:29]
	v_pk_mul_f32 v[200:201], v[54:55], v[30:31]
	v_pk_mul_f32 v[202:203], v[48:49], v[24:25]
	v_pk_mul_f32 v[204:205], v[50:51], v[26:27]
	v_pk_add_f32 v[190:191], v[190:191], v[188:189]
	v_pk_add_f32 v[192:193], v[192:193], v[188:189]
	v_pk_add_f32 v[194:195], v[194:195], v[188:189]
	v_pk_add_f32 v[196:197], v[196:197], v[188:189]
	v_rcp_f32_e32 v190, v190
	v_rcp_f32_e32 v191, v191
	v_rcp_f32_e32 v192, v192
	v_rcp_f32_e32 v193, v193
	v_rcp_f32_e32 v194, v194
	v_rcp_f32_e32 v195, v195
	v_rcp_f32_e32 v196, v196
	v_rcp_f32_e32 v197, v197
	v_pk_mul_f32 v[198:199], v[198:199], v[186:187] op_sel_hi:[1,0]
	v_pk_mul_f32 v[200:201], v[200:201], v[186:187] op_sel_hi:[1,0]
	v_pk_mul_f32 v[202:203], v[202:203], v[186:187] op_sel_hi:[1,0]
	v_pk_mul_f32 v[204:205], v[204:205], v[186:187] op_sel_hi:[1,0]
	v_pk_mul_f32 v[198:199], v[198:199], v[190:191]
	v_pk_mul_f32 v[200:201], v[200:201], v[192:193]
	v_pk_mul_f32 v[202:203], v[202:203], v[194:195]
	v_pk_mul_f32 v[204:205], v[204:205], v[196:197]
	v_cvt_pk_bf16_f32 v132, v198, v199
	v_cvt_pk_bf16_f32 v133, v200, v201
	v_cvt_pk_bf16_f32 v134, v202, v203
	v_cvt_pk_bf16_f32 v135, v204, v205
	flat_store_dwordx4 v[172:173], v[132:135]
	v_fmamk_f32 v206, v253, 0x3a800000, v237
	v_rsq_f32_e32 v182, v206
	v_mad_i64_i32 v[172:173], s[38:39], s82, v166, 0
	v_lshl_add_u64 v[172:173], v[172:173], 1, s[84:85]
	v_lshl_add_u64 v[172:173], v[172:173], 0, s[6:7]
	v_lshl_add_u64 v[172:173], v[172:173], 0, v[128:129]
	v_mul_f32_e32 v184, 0xbfb8aa3b, v182
	v_mul_f32_e32 v186, v182, v182
	v_pk_mul_f32 v[190:191], v[36:37], v[184:185] op_sel_hi:[1,0]
	v_pk_mul_f32 v[192:193], v[38:39], v[184:185] op_sel_hi:[1,0]
	v_pk_mul_f32 v[194:195], v[32:33], v[184:185] op_sel_hi:[1,0]
	v_pk_mul_f32 v[196:197], v[34:35], v[184:185] op_sel_hi:[1,0]
	v_exp_f32_e32 v190, v190
	v_exp_f32_e32 v191, v191
	v_exp_f32_e32 v192, v192
	v_exp_f32_e32 v193, v193
	v_exp_f32_e32 v194, v194
	v_exp_f32_e32 v195, v195
	v_exp_f32_e32 v196, v196
	v_exp_f32_e32 v197, v197
	v_pk_mul_f32 v[198:199], v[36:37], v[12:13]
	v_pk_mul_f32 v[200:201], v[38:39], v[14:15]
	v_pk_mul_f32 v[202:203], v[32:33], v[8:9]
	v_pk_mul_f32 v[204:205], v[34:35], v[10:11]
	v_pk_add_f32 v[190:191], v[190:191], v[188:189]
	v_pk_add_f32 v[192:193], v[192:193], v[188:189]
	v_pk_add_f32 v[194:195], v[194:195], v[188:189]
	v_pk_add_f32 v[196:197], v[196:197], v[188:189]
	v_rcp_f32_e32 v190, v190
	v_rcp_f32_e32 v191, v191
	v_rcp_f32_e32 v192, v192
	v_rcp_f32_e32 v193, v193
	v_rcp_f32_e32 v194, v194
	v_rcp_f32_e32 v195, v195
	v_rcp_f32_e32 v196, v196
	v_rcp_f32_e32 v197, v197
	v_pk_mul_f32 v[198:199], v[198:199], v[186:187] op_sel_hi:[1,0]
	v_pk_mul_f32 v[200:201], v[200:201], v[186:187] op_sel_hi:[1,0]
	v_pk_mul_f32 v[202:203], v[202:203], v[186:187] op_sel_hi:[1,0]
	v_pk_mul_f32 v[204:205], v[204:205], v[186:187] op_sel_hi:[1,0]
	v_pk_mul_f32 v[198:199], v[198:199], v[190:191]
	v_pk_mul_f32 v[200:201], v[200:201], v[192:193]
	v_pk_mul_f32 v[202:203], v[202:203], v[194:195]
	v_pk_mul_f32 v[204:205], v[204:205], v[196:197]
	v_cvt_pk_bf16_f32 v132, v198, v199
	v_cvt_pk_bf16_f32 v133, v200, v201
	v_cvt_pk_bf16_f32 v134, v202, v203
	v_cvt_pk_bf16_f32 v135, v204, v205
	flat_store_dwordx4 v[172:173], v[132:135]
	v_fmamk_f32 v206, v255, 0x3a800000, v237
	v_rsq_f32_e32 v182, v206
	v_mad_i64_i32 v[172:173], s[38:39], s82, v165, 0
	v_lshl_add_u64 v[172:173], v[172:173], 1, s[84:85]
	v_lshl_add_u64 v[172:173], v[172:173], 0, s[6:7]
	v_lshl_add_u64 v[172:173], v[172:173], 0, v[128:129]
	v_mul_f32_e32 v184, 0xbfb8aa3b, v182
	v_mul_f32_e32 v186, v182, v182
	v_pk_mul_f32 v[190:191], v[20:21], v[184:185] op_sel_hi:[1,0]
	v_pk_mul_f32 v[192:193], v[22:23], v[184:185] op_sel_hi:[1,0]
	v_pk_mul_f32 v[194:195], v[16:17], v[184:185] op_sel_hi:[1,0]
	v_pk_mul_f32 v[196:197], v[18:19], v[184:185] op_sel_hi:[1,0]
	v_exp_f32_e32 v190, v190
	v_exp_f32_e32 v191, v191
	v_exp_f32_e32 v192, v192
	v_exp_f32_e32 v193, v193
	v_exp_f32_e32 v194, v194
	v_exp_f32_e32 v195, v195
	v_exp_f32_e32 v196, v196
	v_exp_f32_e32 v197, v197
	v_pk_mul_f32 v[198:199], v[20:21], v[4:5]
	v_pk_mul_f32 v[200:201], v[22:23], v[6:7]
	v_pk_mul_f32 v[202:203], v[16:17], v[0:1]
	v_pk_mul_f32 v[204:205], v[18:19], v[2:3]
	v_pk_add_f32 v[190:191], v[190:191], v[188:189]
	v_pk_add_f32 v[192:193], v[192:193], v[188:189]
	v_pk_add_f32 v[194:195], v[194:195], v[188:189]
	v_pk_add_f32 v[196:197], v[196:197], v[188:189]
	v_rcp_f32_e32 v190, v190
	v_rcp_f32_e32 v191, v191
	v_rcp_f32_e32 v192, v192
	v_rcp_f32_e32 v193, v193
	v_rcp_f32_e32 v194, v194
	v_rcp_f32_e32 v195, v195
	v_rcp_f32_e32 v196, v196
	v_rcp_f32_e32 v197, v197
	v_pk_mul_f32 v[198:199], v[198:199], v[186:187] op_sel_hi:[1,0]
	v_pk_mul_f32 v[200:201], v[200:201], v[186:187] op_sel_hi:[1,0]
	v_pk_mul_f32 v[202:203], v[202:203], v[186:187] op_sel_hi:[1,0]
	v_pk_mul_f32 v[204:205], v[204:205], v[186:187] op_sel_hi:[1,0]
	v_pk_mul_f32 v[198:199], v[198:199], v[190:191]
	v_pk_mul_f32 v[200:201], v[200:201], v[192:193]
	v_pk_mul_f32 v[202:203], v[202:203], v[194:195]
	v_pk_mul_f32 v[204:205], v[204:205], v[196:197]
	v_cvt_pk_bf16_f32 v132, v198, v199
	v_cvt_pk_bf16_f32 v133, v200, v201
	v_cvt_pk_bf16_f32 v134, v202, v203
	v_cvt_pk_bf16_f32 v135, v204, v205
	s_mov_b64 s[6:7], 0
	flat_store_dwordx4 v[172:173], v[132:135]
